# grid barrier: single agent-scope L1 invalidate per workgroup issued right after the opening s_barrier (overlaps the arrival atomic); none after the release
# baseline (speedup 1.0000x reference)
; __device__ __forceinline__ void xcd_barrier(const XcdBarrier& b) {
;     asm volatile("s_waitcnt vmcnt(0)" ::: "memory");
;     __syncthreads();
;     if (threadIdx.x == 0) {
;         unsigned* bar = b.bar;
;         __builtin_amdgcn_s_waitcnt(0);
;         unsigned nloc = b.st[0], nx = b.st[1];
;         if (nloc == 0u) { xcd_barrier_complete(bar, b.x, nloc, nx); b.st[0] = nloc; b.st[1] = nx; }
.LBB0_1129:
	s_and_b64 vcc, exec, s[16:17]
	s_cbranch_vccz .LBB0_18
	s_waitcnt vmcnt(0)
	s_waitcnt vmcnt(0)
	s_barrier
	s_and_saveexec_b64 s[16:17], s[96:97]
	s_cbranch_execz .LBB0_17
	buffer_inv sc1
	v_readlane_b32 s2, v254, 50
	s_waitcnt expcnt(0) lgkmcnt(0)

; __device__ __forceinline__ unsigned xb_ld(unsigned* p)              { return __hip_atomic_load(p, __ATOMIC_RELAXED, __HIP_MEMORY_SCOPE_AGENT); }
; __device__ __forceinline__ void xcd_barrier_complete(unsigned* bar, unsigned x, unsigned& nloc, unsigned& nx) {
;     ...
;     for (;;) {
;         sum = 0u; cnt = 0u; mine = 0u;
; #pragma unroll
;         for (unsigned j = 0; j < 16; ++j) { const unsigned c = xb_ld(&bar[XB_XCNT(j)]); sum += c; cnt += (c > 0u) ? 1u : 0u; mine = (j == x) ? c : mine; }
;         if (sum == G) break;
; __device__ __forceinline__ void xcd_barrier(const XcdBarrier& b) {
;     ...
;         unsigned nloc = b.st[0], nx = b.st[1];
;         if (nloc == 0u) { xcd_barrier_complete(bar, b.x, nloc, nx); b.st[0] = nloc; b.st[1] = nx; }
	s_nop 0
	v_mov_b32_e32 v0, s2
	ds_read_b32 v2, v0
	v_readlane_b32 s2, v254, 51
	s_waitcnt lgkmcnt(0)
	v_cmp_ne_u32_e32 vcc, 0, v2
	v_mov_b32_e32 v0, s2
	ds_read_b32 v0, v0
	s_cbranch_vccnz .LBB0_1146
	s_mov_b32 s4, 1
	s_branch .LBB0_1134
